# NSA top-16 by exact threshold search (31-step ballot+popcount on the ordered score bits, 4 rows interleaved) instead of the all-pairs rank loop
# speedup vs baseline: 1.0160x; 1.0040x over previous
.LBB0_308:
	s_or_b64 exec, exec, s[0:1]
	s_waitcnt lgkmcnt(0)
	v_cmp_eq_u32_e32 vcc, s67, v168
	s_or_b64 s[0:1], s[6:7], vcc
	v_cmp_eq_u32_e32 vcc, s67, v207
	s_or_b64 vcc, s[0:1], vcc
	v_cmp_lt_i32_e64 s[0:1], s67, v168
	ds_read_b32 v0, v206 offset:36864
	ds_read_b32 v34, v206 offset:37120
	ds_read_b32 v35, v206 offset:37376
	ds_read_b32 v226, v206 offset:37632
	s_mov_b32 s28, 0
	s_mov_b32 s29, 0
	s_mov_b32 s30, 0
	s_mov_b32 s31, 0
	s_mov_b32 s18, 0x40000000
	s_waitcnt lgkmcnt(0)
	v_cndmask_b32_e32 v0, v0, v231, vcc
	v_cndmask_b32_e32 v34, v34, v231, vcc
	v_cndmask_b32_e32 v35, v35, v231, vcc
	v_cndmask_b32_e32 v226, v226, v231, vcc
	v_and_b32_e32 v0, 0x7fffffff, v0
	v_and_b32_e32 v34, 0x7fffffff, v34
	v_and_b32_e32 v35, 0x7fffffff, v35
	v_and_b32_e32 v226, 0x7fffffff, v226
	v_cndmask_b32_e64 v0, v0, -1.0, s[0:1]
	v_cndmask_b32_e64 v34, v34, -1.0, s[0:1]
	v_cndmask_b32_e64 v35, v35, -1.0, s[0:1]
	v_cndmask_b32_e64 v226, v226, -1.0, s[0:1]
.Ltopk_a:
	s_or_b32 s10, s28, s18
	s_or_b32 s11, s29, s18
	s_or_b32 s8, s30, s18
	s_or_b32 s9, s31, s18
	v_cmp_le_i32_e64 s[20:21], s10, v0
	v_cmp_le_i32_e64 s[86:87], s11, v34
	v_cmp_le_i32_e64 s[24:25], s8, v35
	v_cmp_le_i32_e64 s[26:27], s9, v226
	s_bcnt1_i32_b64 s101, s[20:21]
	s_cmp_ge_u32 s101, 16
	s_cselect_b32 s28, s10, s28
	s_bcnt1_i32_b64 s101, s[86:87]
	s_cmp_ge_u32 s101, 16
	s_cselect_b32 s29, s11, s29
	s_bcnt1_i32_b64 s101, s[24:25]
	s_cmp_ge_u32 s101, 16
	s_cselect_b32 s30, s8, s30
	s_bcnt1_i32_b64 s101, s[26:27]
	s_cmp_ge_u32 s101, 16
	s_cselect_b32 s31, s9, s31
	s_lshr_b32 s18, s18, 1
	s_cmp_lg_u32 s18, 0
	s_cbranch_scc1 .Ltopk_a
	v_cmp_lt_i32_e64 s[20:21], s28, v0
	v_cmp_eq_u32_e64 s[10:11], s28, v0
	s_bcnt1_i32_b64 s101, s[20:21]
	s_sub_i32 s101, 16, s101
	s_nop 0
	v_mbcnt_lo_u32_b32 v227, s10, 0
	v_mbcnt_hi_u32_b32 v227, s11, v227
	v_cmp_gt_u32_e64 s[8:9], s101, v227
	s_and_b64 s[10:11], s[10:11], s[8:9]
	s_or_b64 s[20:21], s[20:21], s[10:11]
	v_cmp_lt_i32_e64 s[86:87], s29, v34
	v_cmp_eq_u32_e64 s[10:11], s29, v34
	s_bcnt1_i32_b64 s101, s[86:87]
	s_sub_i32 s101, 16, s101
	s_nop 0
	v_mbcnt_lo_u32_b32 v227, s10, 0
	v_mbcnt_hi_u32_b32 v227, s11, v227
	v_cmp_gt_u32_e64 s[8:9], s101, v227
	s_and_b64 s[10:11], s[10:11], s[8:9]
	s_or_b64 s[86:87], s[86:87], s[10:11]
	v_cmp_lt_i32_e64 s[24:25], s30, v35
	v_cmp_eq_u32_e64 s[10:11], s30, v35
	s_bcnt1_i32_b64 s101, s[24:25]
	s_sub_i32 s101, 16, s101
	s_nop 0
	v_mbcnt_lo_u32_b32 v227, s10, 0
	v_mbcnt_hi_u32_b32 v227, s11, v227
	v_cmp_gt_u32_e64 s[8:9], s101, v227
	s_and_b64 s[10:11], s[10:11], s[8:9]
	s_or_b64 s[24:25], s[24:25], s[10:11]
	v_cmp_lt_i32_e64 s[26:27], s31, v226
	v_cmp_eq_u32_e64 s[10:11], s31, v226
	s_bcnt1_i32_b64 s101, s[26:27]
	s_sub_i32 s101, 16, s101
	s_nop 0
	v_mbcnt_lo_u32_b32 v227, s10, 0
	v_mbcnt_hi_u32_b32 v227, s11, v227
	v_cmp_gt_u32_e64 s[8:9], s101, v227
	s_and_b64 s[10:11], s[10:11], s[8:9]
	s_or_b64 s[26:27], s[26:27], s[10:11]
	s_and_saveexec_b64 s[12:13], s[6:7]
	v_mov_b32_e32 v0, s70
	v_mov_b64_e32 v[34:35], s[20:21]
	ds_write_b64 v0, v[34:35] offset:53248
	v_mov_b64_e32 v[226:227], s[86:87]
	ds_write_b64 v0, v[226:227] offset:53256
	v_mov_b64_e32 v[34:35], s[24:25]
	ds_write_b64 v0, v[34:35] offset:53264
	v_mov_b64_e32 v[226:227], s[26:27]
	ds_write_b64 v0, v[226:227] offset:53272
	s_or_b64 exec, exec, s[12:13]
	v_writelane_b32 v250, s20, 0
	v_writelane_b32 v250, s21, 1
	v_writelane_b32 v250, s86, 2
	v_writelane_b32 v250, s87, 3
	v_writelane_b32 v250, s24, 4
	v_writelane_b32 v250, s25, 5
	v_writelane_b32 v250, s26, 6
	v_writelane_b32 v250, s27, 7
	ds_read_b32 v0, v206 offset:37888
	ds_read_b32 v34, v206 offset:38144
	ds_read_b32 v35, v206 offset:38400
	ds_read_b32 v226, v206 offset:38656
	s_mov_b32 s20, 0
	s_mov_b32 s21, 0
	s_mov_b32 s86, 0
	s_mov_b32 s87, 0
	s_mov_b32 s18, 0x40000000
	s_waitcnt lgkmcnt(0)
	v_cndmask_b32_e32 v0, v0, v231, vcc
	v_cndmask_b32_e32 v34, v34, v231, vcc
	v_cndmask_b32_e32 v35, v35, v231, vcc
	v_cndmask_b32_e32 v226, v226, v231, vcc
	v_and_b32_e32 v0, 0x7fffffff, v0
	v_and_b32_e32 v34, 0x7fffffff, v34
	v_and_b32_e32 v35, 0x7fffffff, v35
	v_and_b32_e32 v226, 0x7fffffff, v226
	v_cndmask_b32_e64 v0, v0, -1.0, s[0:1]
	v_cndmask_b32_e64 v34, v34, -1.0, s[0:1]
	v_cndmask_b32_e64 v35, v35, -1.0, s[0:1]
	v_cndmask_b32_e64 v226, v226, -1.0, s[0:1]
.Ltopk_b:
	s_or_b32 s24, s20, s18
	s_or_b32 s25, s21, s18
	s_or_b32 s26, s86, s18
	s_or_b32 s27, s87, s18
	v_cmp_le_i32_e64 s[28:29], s24, v0
	v_cmp_le_i32_e64 s[30:31], s25, v34
	v_cmp_le_i32_e64 s[10:11], s26, v35
	v_cmp_le_i32_e64 s[8:9], s27, v226
	s_bcnt1_i32_b64 s101, s[28:29]
	s_cmp_ge_u32 s101, 16
	s_cselect_b32 s20, s24, s20
	s_bcnt1_i32_b64 s101, s[30:31]
	s_cmp_ge_u32 s101, 16
	s_cselect_b32 s21, s25, s21
	s_bcnt1_i32_b64 s101, s[10:11]
	s_cmp_ge_u32 s101, 16
	s_cselect_b32 s86, s26, s86
	s_bcnt1_i32_b64 s101, s[8:9]
	s_cmp_ge_u32 s101, 16
	s_cselect_b32 s87, s27, s87
	s_lshr_b32 s18, s18, 1
	s_cmp_lg_u32 s18, 0
	s_cbranch_scc1 .Ltopk_b
	v_cmp_lt_i32_e64 s[28:29], s20, v0
	v_cmp_eq_u32_e64 s[24:25], s20, v0
	s_bcnt1_i32_b64 s101, s[28:29]
	s_sub_i32 s101, 16, s101
	s_nop 0
	v_mbcnt_lo_u32_b32 v227, s24, 0
	v_mbcnt_hi_u32_b32 v227, s25, v227
	v_cmp_gt_u32_e64 s[26:27], s101, v227
	s_and_b64 s[24:25], s[24:25], s[26:27]
	s_or_b64 s[28:29], s[28:29], s[24:25]
	v_cmp_lt_i32_e64 s[30:31], s21, v34
	v_cmp_eq_u32_e64 s[24:25], s21, v34
	s_bcnt1_i32_b64 s101, s[30:31]
	s_sub_i32 s101, 16, s101
	s_nop 0
	v_mbcnt_lo_u32_b32 v227, s24, 0
	v_mbcnt_hi_u32_b32 v227, s25, v227
	v_cmp_gt_u32_e64 s[26:27], s101, v227
	s_and_b64 s[24:25], s[24:25], s[26:27]
	s_or_b64 s[30:31], s[30:31], s[24:25]
	v_cmp_lt_i32_e64 s[10:11], s86, v35
	v_cmp_eq_u32_e64 s[24:25], s86, v35
	s_bcnt1_i32_b64 s101, s[10:11]
	s_sub_i32 s101, 16, s101
	s_nop 0
	v_mbcnt_lo_u32_b32 v227, s24, 0
	v_mbcnt_hi_u32_b32 v227, s25, v227
	v_cmp_gt_u32_e64 s[26:27], s101, v227
	s_and_b64 s[24:25], s[24:25], s[26:27]
	s_or_b64 s[10:11], s[10:11], s[24:25]
	v_cmp_lt_i32_e64 s[8:9], s87, v226
	v_cmp_eq_u32_e64 s[24:25], s87, v226
	s_bcnt1_i32_b64 s101, s[8:9]
	s_sub_i32 s101, 16, s101
	s_nop 0
	v_mbcnt_lo_u32_b32 v227, s24, 0
	v_mbcnt_hi_u32_b32 v227, s25, v227
	v_cmp_gt_u32_e64 s[26:27], s101, v227
	s_and_b64 s[24:25], s[24:25], s[26:27]
	s_or_b64 s[8:9], s[8:9], s[24:25]
	s_and_saveexec_b64 s[12:13], s[6:7]
	v_mov_b32_e32 v0, s70
	v_mov_b64_e32 v[34:35], s[28:29]
	ds_write_b64 v0, v[34:35] offset:53280
	v_mov_b64_e32 v[226:227], s[30:31]
	ds_write_b64 v0, v[226:227] offset:53288
	v_mov_b64_e32 v[34:35], s[10:11]
	ds_write_b64 v0, v[34:35] offset:53296
	v_mov_b64_e32 v[226:227], s[8:9]
	ds_write_b64 v0, v[226:227] offset:53304
	s_or_b64 exec, exec, s[12:13]
	v_readlane_b32 s20, v250, 0
	v_readlane_b32 s21, v250, 1
	v_readlane_b32 s86, v250, 2
	v_readlane_b32 s87, v250, 3
	v_readlane_b32 s24, v250, 4
	v_readlane_b32 s25, v250, 5
	v_readlane_b32 s26, v250, 6
	v_readlane_b32 s27, v250, 7
	s_and_saveexec_b64 s[0:1], s[6:7]
	s_cbranch_execz .LBB0_345
	s_or_b64 s[12:13], s[86:87], s[20:21]
	s_or_b64 s[12:13], s[12:13], s[24:25]
	s_or_b64 s[12:13], s[12:13], s[26:27]
	s_or_b64 s[12:13], s[12:13], s[28:29]
	s_or_b64 s[12:13], s[12:13], s[30:31]
	v_mbcnt_lo_u32_b32 v0, exec_lo, 0
	s_or_b64 s[10:11], s[12:13], s[10:11]
	v_mbcnt_hi_u32_b32 v0, exec_hi, v0
	s_or_b64 s[8:9], s[10:11], s[8:9]
	v_cmp_eq_u32_e32 vcc, 0, v0
	s_and_saveexec_b64 s[10:11], vcc
	v_mov_b32_e32 v0, s8
	ds_or_b32 v1, v0 offset:53760
	s_or_b64 exec, exec, s[10:11]
	v_mbcnt_lo_u32_b32 v0, exec_lo, 0
	v_mbcnt_hi_u32_b32 v0, exec_hi, v0
	v_cmp_eq_u32_e32 vcc, 0, v0
	s_and_b64 exec, exec, vcc
	v_mov_b32_e32 v0, s9
	ds_or_b32 v1, v0 offset:53764
